# phase-8 rebalance + gridDim==256 guards on remap/wait (robustness)
# baseline (speedup 1.0000x reference)
.LBB0_1607:
	s_add_i32 s26, s26, 1
	s_mul_i32 s4, s26, s41
	s_mul_hi_u32 s5, s26, s78
	s_add_i32 s5, s5, s4
	s_mul_i32 s4, s26, s78
	s_add_u32 s4, s4, s33
	s_addc_u32 s5, s5, s91
	s_cmp_lg_u32 s66, 4
	s_cbranch_scc1 .Lmy_p8_map_done
	s_cmp_lg_u32 s78, 0x100
	s_cbranch_scc1 .Lmy_p8_map_done
	s_movk_i32 s18, 0x80
	s_cmp_lt_i32 s33, 0x80
	s_cbranch_scc1 .Lmy_p8_pos
	s_movk_i32 s18, 0xff80

.LBB0_1632:
	s_andn2_b64 vcc, exec, s[6:7]
	s_cbranch_vccnz .LBB0_1634
	s_cmp_eq_u32 s26, 2
	s_cbranch_scc0 .Lmy_p8_nowait
	s_cmp_eq_u32 s78, 0x100
	s_cbranch_scc0 .Lmy_p8_nowait
	s_cmp_gt_u32 s74, 0x7f
	s_cbranch_scc0 .Lmy_p8_nowait
	v_cmp_eq_u32_e32 vcc, 0, v202
	s_and_saveexec_b64 s[10:11], vcc
	s_cbranch_execz .Lmy_p8_waited
	v_readlane_b32 s8, v253, 2
	v_readlane_b32 s9, v253, 3
	s_sub_i32 s6, s74, 0x80
	s_lshl_b32 s6, s6, 2
	s_add_i32 s6, s6, 0x80000
	v_mov_b32_e32 v242, s6
	s_mov_b32 s7, 0x100000
	s_nop 4
